# strategy 7 instruction selection: 57 packed v_pk_add/mul_f32 in the hg_sequence chunk loop replaced by scalar f32 pairs (packed f32 is slow on this chip)
# speedup vs baseline: 1.0030x; 1.0030x over previous
.LBB0_1409:
	v_add_u32_e32 v0, s82, v67
	v_bfe_u32 v62, v58, 16, 1
	s_movk_i32 s26, 0x7fff
	v_add3_u32 v58, v58, v62, s26
	v_mad_u32_u24 v62, v0, s73, v66
	v_bfe_u32 v0, v59, 16, 1
	v_add3_u32 v0, v59, v0, s26
	ds_write_b16_d16_hi v62, v0 offset:144
	v_bfe_u32 v0, v60, 16, 1
	v_add3_u32 v0, v60, v0, s26
	ds_write_b16_d16_hi v62, v0 offset:288
	v_bfe_u32 v0, v61, 16, 1
	v_add3_u32 v0, v61, v0, s26
	ds_write_b16_d16_hi v62, v0 offset:432
	v_add_u32_e32 v0, s56, v99
	v_mul_u32_u24_e32 v0, s73, v0
	s_add_i32 s2, 0, 0x15200
	v_lshlrev_b32_e32 v94, 4, v100
	v_add3_u32 v0, s2, v0, v94
	s_add_i32 s2, 0, 0x1e200
	v_add_u32_e32 v95, s2, v94
	s_movk_i32 s2, 0x110
	v_lshlrev_b32_e32 v86, 3, v100
	v_mul_u32_u24_e32 v87, s2, v99
	v_add3_u32 v97, 0, v86, v87
	ds_write_b16_d16_hi v62, v58
	v_add_u32_e32 v96, 0x6000, v97
	v_add_f32_e32 v84, v84, v64
	v_add_f32_e32 v85, v85, v65
	s_waitcnt lgkmcnt(0)
	s_barrier
	v_cvt_pk_bf16_f32 v78, v50, v51
	v_cvt_pk_bf16_f32 v79, v52, v53
	v_cvt_pk_bf16_f32 v80, v54, v55
	v_cvt_pk_bf16_f32 v81, v56, v57
	v_cvt_pk_bf16_f32 v74, v42, v43
	v_cvt_pk_bf16_f32 v75, v44, v45
	v_cvt_pk_bf16_f32 v76, v46, v47
	v_cvt_pk_bf16_f32 v77, v48, v49
	v_cvt_pk_bf16_f32 v70, v30, v31
	v_cvt_pk_bf16_f32 v71, v32, v33
	v_cvt_pk_bf16_f32 v72, v38, v39
	v_cvt_pk_bf16_f32 v73, v40, v41
	v_cvt_pk_bf16_f32 v66, v26, v27
	v_cvt_pk_bf16_f32 v67, v28, v29
	v_cvt_pk_bf16_f32 v68, v34, v35
	v_cvt_pk_bf16_f32 v69, v36, v37
	ds_read_b128 v[62:65], v0
	ds_read_b128 v[58:61], v0 offset:64
	ds_read2_b64 v[128:131], v96 offset0:128 offset1:132
	ds_read2_b64 v[132:135], v96 offset0:136 offset1:140
	ds_read2_b64 v[136:139], v96 offset0:144 offset1:148
	ds_read2_b64 v[140:143], v96 offset0:152 offset1:156
	v_lshl_add_u32 v0, v100, 12, v99
	v_mul_u32_u24_e32 v96, s73, v99
	v_add_u32_e32 v108, 0x7000, v97
	v_add_u32_e32 v127, v95, v96
	ds_read_b128 v[144:147], v127
	ds_read_b128 v[148:151], v127 offset:64
	ds_read2_b64 v[152:155], v108 offset0:160 offset1:164
	ds_read2_b64 v[156:159], v108 offset0:168 offset1:172
	ds_read2_b64 v[160:163], v108 offset0:176 offset1:180
	ds_read2_b64 v[164:167], v108 offset0:184 offset1:188
	ds_read_b128 v[168:171], v127 offset:2304
	ds_read_b128 v[172:175], v127 offset:2368
	s_waitcnt lgkmcnt(11)
	v_mfma_f32_16x16x32_bf16 v[86:89], v[128:131], v[78:81], 0
	s_waitcnt lgkmcnt(10)
	v_mfma_f32_16x16x32_bf16 v[86:89], v[132:135], v[74:77], v[86:89]
	s_waitcnt lgkmcnt(9)
	v_mfma_f32_16x16x32_bf16 v[86:89], v[136:139], v[70:73], v[86:89]
	s_waitcnt lgkmcnt(8)
	v_mfma_f32_16x16x32_bf16 v[86:89], v[140:143], v[66:69], v[86:89]
	s_waitcnt lgkmcnt(7)
	v_mfma_f32_16x16x32_bf16 v[86:89], v[144:147], v[62:65], v[86:89]
	s_waitcnt lgkmcnt(6)
	v_mfma_f32_16x16x32_bf16 v[100:103], v[148:151], v[58:61], v[86:89]
	v_add_u32_e32 v99, 0x8000, v97
	ds_read2_b64 v[128:131], v99 offset0:192 offset1:196
	ds_read2_b64 v[132:135], v99 offset0:200 offset1:204
	ds_read2_b64 v[136:139], v99 offset0:208 offset1:212
	ds_read2_b64 v[140:143], v99 offset0:216 offset1:220
	ds_read_b128 v[144:147], v127 offset:4608
	ds_read_b128 v[148:151], v127 offset:4672
	v_lshlrev_b32_e32 v86, 2, v0
	s_add_u32 s2, s74, 0xfffd0000
	s_addc_u32 s3, s75, -1
	v_add_u32_e32 v86, 0x1000, v86
	v_add_u32_e32 v87, 0x2000, v86
	global_store_dword v86, v100, s[2:3] offset:-4096
	global_store_dword v86, v101, s[2:3]
	global_store_dword v87, v102, s[2:3] offset:-4096
	global_store_dword v87, v103, s[2:3]
	s_waitcnt lgkmcnt(11)
	v_mfma_f32_16x16x32_bf16 v[100:103], v[152:155], v[78:81], 0
	s_waitcnt lgkmcnt(10)
	v_mfma_f32_16x16x32_bf16 v[100:103], v[156:159], v[74:77], v[100:103]
	s_waitcnt lgkmcnt(9)
	v_mfma_f32_16x16x32_bf16 v[100:103], v[160:163], v[70:73], v[100:103]
	s_waitcnt lgkmcnt(8)
	v_mfma_f32_16x16x32_bf16 v[100:103], v[164:167], v[66:69], v[100:103]
	s_waitcnt lgkmcnt(7)
	v_mfma_f32_16x16x32_bf16 v[100:103], v[168:171], v[62:65], v[100:103]
	s_waitcnt lgkmcnt(6)
	v_mfma_f32_16x16x32_bf16 v[100:103], v[172:175], v[58:61], v[100:103]
	v_add_u32_e32 v97, 0x9000, v97
	ds_read2_b64 v[152:155], v97 offset0:224 offset1:228
	ds_read2_b64 v[156:159], v97 offset0:232 offset1:236
	ds_read2_b64 v[160:163], v97 offset0:240 offset1:244
	ds_read2_b64 v[164:167], v97 offset0:248 offset1:252
	ds_read_b128 v[168:171], v127 offset:6912
	ds_read_b128 v[172:175], v127 offset:6976
	s_add_u32 s2, s74, 0xfffe0000
	s_addc_u32 s3, s75, -1
	global_store_dword v86, v100, s[2:3] offset:-4096
	global_store_dword v86, v101, s[2:3]
	global_store_dword v87, v102, s[2:3] offset:-4096
	global_store_dword v87, v103, s[2:3]
	s_waitcnt lgkmcnt(11)
	v_mfma_f32_16x16x32_bf16 v[100:103], v[128:131], v[78:81], 0
	s_waitcnt lgkmcnt(10)
	v_mfma_f32_16x16x32_bf16 v[100:103], v[132:135], v[74:77], v[100:103]
	s_waitcnt lgkmcnt(9)
	v_mfma_f32_16x16x32_bf16 v[100:103], v[136:139], v[70:73], v[100:103]
	s_waitcnt lgkmcnt(8)
	v_mfma_f32_16x16x32_bf16 v[100:103], v[140:143], v[66:69], v[100:103]
	s_waitcnt lgkmcnt(7)
	v_mfma_f32_16x16x32_bf16 v[100:103], v[144:147], v[62:65], v[100:103]
	s_waitcnt lgkmcnt(6)
	v_mfma_f32_16x16x32_bf16 v[100:103], v[148:151], v[58:61], v[100:103]
	v_add_u32_e32 v127, 0x19a00, v94
	v_add_u32_e32 v127, v127, v96
	ds_read_b128 v[128:131], v94 offset:6144
	ds_read_b128 v[132:135], v127
	ds_read_b128 v[136:139], v127 offset:64
	ds_read_b128 v[140:143], v94 offset:6208
	ds_read_b128 v[144:147], v127 offset:2304
	ds_read_b128 v[148:151], v127 offset:2368
	s_add_u32 s2, s74, 0xffff0000
	s_addc_u32 s3, s75, -1
	global_store_dword v86, v100, s[2:3] offset:-4096
	global_store_dword v86, v101, s[2:3]
	global_store_dword v87, v102, s[2:3] offset:-4096
	global_store_dword v87, v103, s[2:3]
	s_waitcnt lgkmcnt(11)
	v_mfma_f32_16x16x32_bf16 v[78:81], v[152:155], v[78:81], 0
	s_waitcnt lgkmcnt(10)
	v_mfma_f32_16x16x32_bf16 v[74:77], v[156:159], v[74:77], v[78:81]
	s_waitcnt lgkmcnt(9)
	v_mfma_f32_16x16x32_bf16 v[70:73], v[160:163], v[70:73], v[74:77]
	s_waitcnt lgkmcnt(8)
	v_mfma_f32_16x16x32_bf16 v[66:69], v[164:167], v[66:69], v[70:73]
	s_waitcnt lgkmcnt(7)
	v_mfma_f32_16x16x32_bf16 v[66:69], v[168:171], v[62:65], v[66:69]
	s_waitcnt lgkmcnt(6)
	v_mfma_f32_16x16x32_bf16 v[66:69], v[172:175], v[58:61], v[66:69]
	ds_read_b128 v[152:155], v94 offset:6272
	ds_read_b128 v[156:159], v127 offset:4608
	ds_read_b128 v[160:163], v127 offset:4672
	ds_read_b128 v[164:167], v94 offset:6336
	ds_read_b128 v[168:171], v127 offset:6912
	ds_read_b128 v[172:175], v127 offset:6976
	s_nop 1
	global_store_dword v86, v66, s[74:75] offset:-4096
	global_store_dword v86, v67, s[74:75]
	global_store_dword v87, v68, s[74:75] offset:-4096
	global_store_dword v87, v69, s[74:75]
	s_add_u32 s34, s34, 0x20000
	s_addc_u32 s35, s35, 0
	s_add_u32 s74, s74, 0x40000
	s_addc_u32 s75, s75, 0
	s_mov_b32 s2, 0x19a00
	s_cmp_eq_u32 s34, 0x400000
	s_waitcnt lgkmcnt(11)
	v_mul_f32_e32 v50, v50, v128
	v_mul_f32_e32 v51, v51, v129
	v_mul_f32_e32 v52, v52, v130
	v_mul_f32_e32 v53, v53, v131
	s_waitcnt lgkmcnt(10)
	s_nop 0
	v_mfma_f32_16x16x32_bf16 v[50:53], v[132:135], v[62:65], v[50:53]
	s_waitcnt lgkmcnt(9)
	v_mfma_f32_16x16x32_bf16 v[50:53], v[136:139], v[58:61], v[50:53]
	ds_read_b128 v[128:131], v94 offset:6400
	ds_read_b128 v[132:135], v127 offset:9216
	ds_read_b128 v[136:139], v127 offset:9280
	s_waitcnt lgkmcnt(11)
	v_mul_f32_e32 v54, v54, v140
	v_mul_f32_e32 v55, v55, v141
	v_mul_f32_e32 v56, v56, v142
	v_mul_f32_e32 v57, v57, v143
	s_waitcnt lgkmcnt(10)
	s_nop 0
	v_mfma_f32_16x16x32_bf16 v[54:57], v[144:147], v[62:65], v[54:57]
	s_waitcnt lgkmcnt(9)
	v_mfma_f32_16x16x32_bf16 v[54:57], v[148:151], v[58:61], v[54:57]
	ds_read_b128 v[140:143], v94 offset:6464
	ds_read_b128 v[144:147], v127 offset:11520
	ds_read_b128 v[148:151], v127 offset:11584
	s_waitcnt lgkmcnt(11)
	v_mul_f32_e32 v42, v42, v152
	v_mul_f32_e32 v43, v43, v153
	v_mul_f32_e32 v44, v44, v154
	v_mul_f32_e32 v45, v45, v155
	s_waitcnt lgkmcnt(10)
	s_nop 0
	v_mfma_f32_16x16x32_bf16 v[42:45], v[156:159], v[62:65], v[42:45]
	s_waitcnt lgkmcnt(9)
	v_mfma_f32_16x16x32_bf16 v[42:45], v[160:163], v[58:61], v[42:45]
	ds_read_b128 v[152:155], v94 offset:6528
	ds_read_b128 v[156:159], v127 offset:13824
	ds_read_b128 v[160:163], v127 offset:13888
	s_waitcnt lgkmcnt(11)
	v_mul_f32_e32 v46, v46, v164
	v_mul_f32_e32 v47, v47, v165
	v_mul_f32_e32 v48, v48, v166
	v_mul_f32_e32 v49, v49, v167
	s_waitcnt lgkmcnt(10)
	s_nop 0
	v_mfma_f32_16x16x32_bf16 v[46:49], v[168:171], v[62:65], v[46:49]
	s_waitcnt lgkmcnt(9)
	v_mfma_f32_16x16x32_bf16 v[46:49], v[172:175], v[58:61], v[46:49]
	ds_read_b128 v[164:167], v94 offset:6592
	ds_read_b128 v[168:171], v127 offset:16128
	ds_read_b128 v[172:175], v127 offset:16192
	s_waitcnt lgkmcnt(11)
	v_mul_f32_e32 v30, v30, v128
	v_mul_f32_e32 v31, v31, v129
	v_mul_f32_e32 v32, v32, v130
	v_mul_f32_e32 v33, v33, v131
	s_waitcnt lgkmcnt(10)
	s_nop 0
	v_mfma_f32_16x16x32_bf16 v[30:33], v[132:135], v[62:65], v[30:33]
	s_waitcnt lgkmcnt(9)
	v_mfma_f32_16x16x32_bf16 v[30:33], v[136:139], v[58:61], v[30:33]
	s_waitcnt lgkmcnt(8)
	v_mul_f32_e32 v38, v38, v140
	v_mul_f32_e32 v39, v39, v141
	v_mul_f32_e32 v40, v40, v142
	v_mul_f32_e32 v41, v41, v143
	s_waitcnt lgkmcnt(7)
	s_nop 0
	v_mfma_f32_16x16x32_bf16 v[38:41], v[144:147], v[62:65], v[38:41]
	s_waitcnt lgkmcnt(6)
	v_mfma_f32_16x16x32_bf16 v[38:41], v[148:151], v[58:61], v[38:41]
	s_waitcnt lgkmcnt(5)
	v_mul_f32_e32 v26, v26, v152
	v_mul_f32_e32 v27, v27, v153
	v_mul_f32_e32 v28, v28, v154
	v_mul_f32_e32 v29, v29, v155
	s_waitcnt lgkmcnt(4)
	s_nop 0
	v_mfma_f32_16x16x32_bf16 v[26:29], v[156:159], v[62:65], v[26:29]
	s_waitcnt lgkmcnt(3)
	v_mfma_f32_16x16x32_bf16 v[26:29], v[160:163], v[58:61], v[26:29]
	s_waitcnt lgkmcnt(2)
	v_mul_f32_e32 v34, v34, v164
	v_mul_f32_e32 v35, v35, v165
	v_mul_f32_e32 v36, v36, v166
	v_mul_f32_e32 v37, v37, v167
	s_waitcnt lgkmcnt(1)
	s_nop 0
	v_mfma_f32_16x16x32_bf16 v[34:37], v[168:171], v[62:65], v[34:37]
	s_waitcnt lgkmcnt(0)
	s_barrier
	v_mfma_f32_16x16x32_bf16 v[34:37], v[172:175], v[58:61], v[34:37]
	s_cbranch_scc1 .LBB0_1472
.LBB0_1410:
	s_waitcnt vmcnt(38)
	v_lshlrev_b32_e32 v101, 16, v16
	v_sub_f32_e32 v128, 1.0, v101
	v_max_f32_e32 v128, 0x3a800000, v128
	s_mov_b32 s2, 0x800000
	s_mov_b32 s3, 0x3f317217
	s_mov_b32 s28, 0x7f800000
	v_log_f32_e32 v128, v128
	v_and_b32_e32 v104, 0xffff0000, v16
	s_waitcnt vmcnt(36)
	v_lshlrev_b32_e32 v102, 16, v17
	v_and_b32_e32 v105, 0xffff0000, v17
	v_mul_f32_e32 v58, 0x3f317217, v128
	v_fma_f32 v58, v128, s3, -v58
	v_fmac_f32_e32 v58, 0x3377d1cf, v128
	v_fmac_f32_e32 v58, 0x3f317217, v128
	s_waitcnt vmcnt(32)
	v_lshlrev_b32_e32 v103, 16, v18
	v_and_b32_e32 v107, 0xffff0000, v18


	v_sub_f32_e32 v129, 1.0, v104
	v_max_f32_e32 v129, 0x3a800000, v129
	s_waitcnt vmcnt(30)
	v_lshlrev_b32_e32 v106, 16, v19
	v_and_b32_e32 v109, 0xffff0000, v19
	v_log_f32_e32 v129, v129
	s_waitcnt vmcnt(26)
	v_lshlrev_b32_e32 v108, 16, v20
	v_and_b32_e32 v112, 0xffff0000, v20
	s_waitcnt vmcnt(24)
	v_lshlrev_b32_e32 v110, 16, v21
	v_mul_f32_e32 v59, 0x3f317217, v129
	v_fma_f32 v59, v129, s3, -v59
	v_fmac_f32_e32 v59, 0x3377d1cf, v129
	v_fmac_f32_e32 v59, 0x3f317217, v129
	v_and_b32_e32 v114, 0xffff0000, v21
	s_waitcnt vmcnt(19)
	v_lshlrev_b32_e32 v113, 16, v22


	v_add_f32_e32 v62, 0, v58
	v_add_f32_e32 v63, 0, v59
	v_sub_f32_e32 v130, 1.0, v102
	v_max_f32_e32 v130, 0x3a800000, v130
	v_and_b32_e32 v116, 0xffff0000, v22
	s_waitcnt vmcnt(18)
	v_lshlrev_b32_e32 v115, 16, v23
	v_log_f32_e32 v130, v130
	v_and_b32_e32 v117, 0xffff0000, v23
	v_mov_b32_e32 v99, v83
	v_mov_b32_e32 v0, v82
	v_mul_f32_e32 v58, 0x3f317217, v130
	v_fma_f32 v58, v130, s3, -v58
	v_fmac_f32_e32 v58, 0x3377d1cf, v130
	v_fmac_f32_e32 v58, 0x3f317217, v130
	v_mov_b32_e32 v100, v98


	v_sub_f32_e32 v131, 1.0, v105
	v_max_f32_e32 v131, 0x3a800000, v131

	v_log_f32_e32 v131, v131
	s_nop 0
	v_mul_f32_e32 v59, 0x3f317217, v131
	v_fma_f32 v59, v131, s3, -v59
	v_fmac_f32_e32 v59, 0x3377d1cf, v131
	v_fmac_f32_e32 v59, 0x3f317217, v131


	v_sub_f32_e32 v132, 1.0, v103
	v_max_f32_e32 v132, 0x3a800000, v132
	v_add_f32_e32 v58, v58, v62
	v_add_f32_e32 v59, v59, v63

	v_log_f32_e32 v132, v132
	s_nop 0
	v_mul_f32_e32 v60, 0x3f317217, v132
	v_fma_f32 v60, v132, s3, -v60
	v_fmac_f32_e32 v60, 0x3377d1cf, v132
	v_fmac_f32_e32 v60, 0x3f317217, v132


	v_sub_f32_e32 v133, 1.0, v107
	v_max_f32_e32 v133, 0x3a800000, v133

	v_log_f32_e32 v133, v133
	s_nop 0
	v_mul_f32_e32 v61, 0x3f317217, v133
	v_fma_f32 v61, v133, s3, -v61
	v_fmac_f32_e32 v61, 0x3377d1cf, v133
	v_fmac_f32_e32 v61, 0x3f317217, v133
	s_nop 1


	v_sub_f32_e32 v134, 1.0, v106
	v_max_f32_e32 v134, 0x3a800000, v134
	v_add_f32_e32 v60, v60, v58
	v_add_f32_e32 v61, v61, v59

	v_log_f32_e32 v134, v134
	s_nop 0
	v_mul_f32_e32 v64, 0x3f317217, v134
	v_fma_f32 v64, v134, s3, -v64
	v_fmac_f32_e32 v64, 0x3377d1cf, v134
	v_fmac_f32_e32 v64, 0x3f317217, v134
	s_nop 1


	v_sub_f32_e32 v135, 1.0, v109
	v_max_f32_e32 v135, 0x3a800000, v135

	v_log_f32_e32 v135, v135
	s_nop 0
	v_mul_f32_e32 v65, 0x3f317217, v135
	v_fma_f32 v65, v135, s3, -v65
	v_fmac_f32_e32 v65, 0x3377d1cf, v135
	v_fmac_f32_e32 v65, 0x3f317217, v135
	s_nop 1


	v_add_f32_e32 v66, v64, v60
	v_add_f32_e32 v67, v65, v61
	v_sub_f32_e32 v136, 1.0, v108
	v_max_f32_e32 v136, 0x3a800000, v136

	v_log_f32_e32 v136, v136
	s_nop 0
	v_mul_f32_e32 v64, 0x3f317217, v136
	v_fma_f32 v64, v136, s3, -v64
	v_fmac_f32_e32 v64, 0x3377d1cf, v136
	v_fmac_f32_e32 v64, 0x3f317217, v136
	s_nop 1


	v_sub_f32_e32 v137, 1.0, v112
	v_max_f32_e32 v137, 0x3a800000, v137

	v_log_f32_e32 v137, v137
	s_nop 0
	v_mul_f32_e32 v65, 0x3f317217, v137
	v_fma_f32 v65, v137, s3, -v65
	v_fmac_f32_e32 v65, 0x3377d1cf, v137
	v_fmac_f32_e32 v65, 0x3f317217, v137
	s_nop 1


	v_add_f32_e32 v68, v64, v66
	v_add_f32_e32 v69, v65, v67
	v_sub_f32_e32 v138, 1.0, v110
	v_max_f32_e32 v138, 0x3a800000, v138

	v_log_f32_e32 v138, v138
	s_nop 0
	v_mul_f32_e32 v64, 0x3f317217, v138
	v_fma_f32 v64, v138, s3, -v64
	v_fmac_f32_e32 v64, 0x3377d1cf, v138
	v_fmac_f32_e32 v64, 0x3f317217, v138
	s_nop 1


	v_sub_f32_e32 v139, 1.0, v114
	v_max_f32_e32 v139, 0x3a800000, v139

	v_log_f32_e32 v139, v139
	s_nop 0
	v_mul_f32_e32 v65, 0x3f317217, v139
	v_fma_f32 v65, v139, s3, -v65
	v_fmac_f32_e32 v65, 0x3377d1cf, v139
	v_fmac_f32_e32 v65, 0x3f317217, v139
	s_nop 1


	v_add_f32_e32 v70, v64, v68
	v_add_f32_e32 v71, v65, v69
	v_sub_f32_e32 v140, 1.0, v113
	v_max_f32_e32 v140, 0x3a800000, v140

	v_log_f32_e32 v140, v140
	s_nop 0
	v_mul_f32_e32 v64, 0x3f317217, v140
	v_fma_f32 v64, v140, s3, -v64
	v_fmac_f32_e32 v64, 0x3377d1cf, v140
	v_fmac_f32_e32 v64, 0x3f317217, v140
	s_nop 1


	v_sub_f32_e32 v141, 1.0, v116
	v_max_f32_e32 v141, 0x3a800000, v141

	v_log_f32_e32 v141, v141
	s_nop 0
	v_mul_f32_e32 v65, 0x3f317217, v141
	v_fma_f32 v65, v141, s3, -v65
	v_fmac_f32_e32 v65, 0x3377d1cf, v141
	v_fmac_f32_e32 v65, 0x3f317217, v141
	s_nop 1


	v_add_f32_e32 v72, v64, v70
	v_add_f32_e32 v73, v65, v71
	v_sub_f32_e32 v142, 1.0, v115
	v_max_f32_e32 v142, 0x3a800000, v142

	v_log_f32_e32 v142, v142
	s_nop 0
	v_mul_f32_e32 v64, 0x3f317217, v142
	v_fma_f32 v64, v142, s3, -v64
	v_fmac_f32_e32 v64, 0x3377d1cf, v142
	v_fmac_f32_e32 v64, 0x3f317217, v142
	s_nop 1


	v_sub_f32_e32 v143, 1.0, v117
	v_max_f32_e32 v143, 0x3a800000, v143

	v_log_f32_e32 v143, v143
	s_nop 0
	v_mul_f32_e32 v65, 0x3f317217, v143
	v_fma_f32 v65, v143, s3, -v65
	v_fmac_f32_e32 v65, 0x3377d1cf, v143
	v_fmac_f32_e32 v65, 0x3f317217, v143
	s_nop 1


	v_add_f32_e32 v74, v64, v72
	v_add_f32_e32 v75, v65, v73
	v_lshlrev_b32_e32 v64, 2, v0
	v_add_u32_e32 v65, s76, v64
	ds_write_b64 v65, v[74:75]
	s_waitcnt lgkmcnt(0)
	s_barrier
	v_add_u32_e32 v111, 0, v64
	ds_read2st64_b64 v[76:79], v111 offset1:1
	ds_read2st64_b64 v[128:131], v111 offset0:2 offset1:3
	ds_read2st64_b64 v[132:135], v111 offset0:4 offset1:5
	ds_read2st64_b64 v[136:139], v111 offset0:6 offset1:7
	s_andn2_b64 vcc, exec, s[58:59]
	s_waitcnt lgkmcnt(3)
	v_add_f32_e32 v64, 0, v76
	v_add_f32_e32 v65, 0, v77
	s_nop 0
	v_add_f32_e32 v80, v64, v78
	v_add_f32_e32 v81, v65, v79
	v_cndmask_b32_e64 v86, 0, v65, s[10:11]
	v_cndmask_b32_e64 v87, 0, v64, s[10:11]
	s_waitcnt lgkmcnt(2)
	v_add_f32_e32 v64, v80, v128
	v_add_f32_e32 v65, v81, v129
	v_cndmask_b32_e64 v76, v87, v80, s[12:13]
	v_cndmask_b32_e64 v77, v86, v81, s[12:13]
	v_cndmask_b32_e64 v86, v77, v65, s[14:15]
	v_cndmask_b32_e64 v87, v76, v64, s[14:15]
	v_add_f32_e32 v94, v64, v130
	v_add_f32_e32 v95, v65, v131
	s_waitcnt lgkmcnt(1)
	v_add_f32_e32 v64, v94, v132
	v_add_f32_e32 v65, v95, v133
	v_cndmask_b32_e64 v76, v87, v94, s[16:17]
	v_cndmask_b32_e64 v77, v86, v95, s[16:17]
	v_cndmask_b32_e64 v77, v77, v65, s[18:19]
	v_cndmask_b32_e64 v76, v76, v64, s[18:19]
	v_add_f32_e32 v96, v64, v134
	v_add_f32_e32 v97, v65, v135
	s_nop 0
	v_cndmask_b32_e64 v88, v76, v96, s[20:21]
	v_cndmask_b32_e64 v89, v77, v97, s[20:21]
	s_waitcnt lgkmcnt(0)
	v_add_f32_e32 v86, v96, v136
	v_add_f32_e32 v87, v97, v137
	s_nop 0
	v_add_f32_e32 v64, v86, v138
	v_add_f32_e32 v65, v87, v139
	v_cndmask_b32_e64 v76, 0, v81, s[8:9]
	v_cndmask_b32_e64 v77, 0, v80, s[8:9]
	v_cndmask_b32_e64 v78, v81, v95, s[8:9]
	v_cndmask_b32_e64 v79, v80, v94, s[8:9]
	v_cndmask_b32_e64 v77, v77, v94, s[6:7]
	v_cndmask_b32_e64 v76, v76, v95, s[6:7]
	v_cndmask_b32_e64 v79, v79, v96, s[6:7]
	v_cndmask_b32_e64 v78, v78, v97, s[6:7]
	v_cndmask_b32_e64 v91, v76, v97, s[24:25]
	v_cndmask_b32_e64 v90, v77, v96, s[24:25]
	v_cndmask_b32_e64 v77, v78, v65, s[24:25]
	v_cndmask_b32_e64 v76, v79, v64, s[24:25]
	v_sub_f32_e32 v78, v80, v76
	v_sub_f32_e32 v79, v81, v77
	v_mul_f32_e32 v92, 0x3fb8aa3b, v90
	v_min_f32_e32 v78, 0, v78
	v_mul_f32_e32 v78, 0x3fb8aa3b, v78
	v_exp_f32_e32 v118, v78
	v_min_f32_e32 v78, 0, v79
	v_mul_f32_e32 v78, 0x3fb8aa3b, v78
	v_exp_f32_e32 v119, v78
	v_cndmask_b32_e64 v79, v89, v87, s[22:23]
	v_cndmask_b32_e64 v78, v88, v86, s[22:23]
	v_sub_f32_e32 v88, v78, v90
	v_sub_f32_e32 v89, v79, v91
	v_mul_f32_e32 v93, 0x3fb8aa3b, v91
	v_add_f32_e32 v62, v62, v88
	v_add_f32_e32 v63, v63, v89
	v_sub_f32_e32 v86, v76, v90
	v_sub_f32_e32 v87, v77, v91
	v_mul_f32_e32 v90, 0x3fb8aa3b, v62
	v_exp_f32_e32 v78, v93
	v_exp_f32_e32 v93, v90
	v_mul_f32_e32 v90, 0x3fb8aa3b, v63
	v_exp_f32_e32 v123, v90
	v_mul_f32_e32 v79, 0x3fb8aa3b, v84
	v_rcp_f32_e32 v90, v93
	v_exp_f32_e32 v80, v92
	v_exp_f32_e32 v92, v79
	v_mul_f32_e32 v79, 0x3fb8aa3b, v85
	v_exp_f32_e32 v122, v79
	v_min_f32_e32 v121, 0x79297b5a, v90
	v_rcp_f32_e32 v90, v123
	v_sub_f32_e32 v62, v86, v62
	v_sub_f32_e32 v63, v87, v63
	v_lshlrev_b32_e32 v79, 1, v0
	v_mul_f32_e32 v62, 0x3fb8aa3b, v62
	v_sub_u32_e32 v120, v111, v79
	v_lshlrev_b32_e32 v81, 16, v8
	v_and_b32_e32 v79, 0xffff0000, v8
	v_exp_f32_e32 v125, v62
	v_mul_f32_e32 v62, 0x3fb8aa3b, v63
	v_min_f32_e32 v124, 0x79297b5a, v90
	v_exp_f32_e32 v126, v62
	v_mul_f32_e32 v90, v92, v80
	v_mul_f32_e32 v91, v93, v81
	v_mul_f32_e32 v92, v122, v78
	v_mul_f32_e32 v93, v123, v79
	v_lshl_add_u32 v63, s39, 1, v120
	v_cvt_pk_bf16_f32 v62, v91, v93
	ds_write_b32 v63, v62 offset:8192
	v_mul_f32_e32 v62, v80, v91
	v_mul_f32_e32 v79, v78, v93
	v_cvt_pk_bf16_f32 v62, v62, v79
	ds_write_b32 v63, v62 offset:25600
	v_mul_f32_e32 v62, v90, v91
	v_mul_f32_e32 v63, v92, v93
	v_cvt_pk_bf16_f32 v79, v62, v63
	v_lshl_add_u64 v[62:63], v[0:1], 1, s[34:35]

	v_mul_f32_e32 v91, v121, v101
	v_mul_f32_e32 v93, v124, v104
	global_store_dword v62, v79, s[52:53]
	v_cvt_pk_bf16_f32 v91, v91, v93
	v_add_u32_e32 v93, s38, v120
	ds_write_b32 v93, v91 offset:43008
	v_cndmask_b32_e64 v91, 0, 1, s[58:59]
	v_mul_f32_e32 v79, v125, v101
	v_mul_f32_e32 v81, v126, v104
	v_cmp_ne_u32_e64 s[26:27], 1, v91
	v_add_u32_e32 v101, s33, v120
	s_cbranch_vccnz .LBB0_1412
	v_mul_f32_e32 v91, v119, v81
	v_mul_f32_e32 v93, v118, v79
	v_cvt_pk_bf16_f32 v91, v93, v91
	ds_write_b32 v101, v91 offset:47360
.LBB0_1412:
	v_sub_f32_e32 v94, v94, v76
	v_sub_f32_e32 v95, v95, v77
	s_andn2_b64 vcc, exec, s[60:61]
	v_min_f32_e32 v91, 0, v94
	v_min_f32_e32 v93, 0, v95
	v_mul_f32_e32 v91, 0x3fb8aa3b, v91
	v_mul_f32_e32 v93, 0x3fb8aa3b, v93
	v_exp_f32_e32 v91, v91
	v_exp_f32_e32 v93, v93
	v_cndmask_b32_e64 v94, 0, 1, s[60:61]
	v_cmp_ne_u32_e64 s[28:29], 1, v94
	s_cbranch_vccnz .LBB0_1414
	v_mul_f32_e32 v94, v93, v81
	v_mul_f32_e32 v95, v91, v79
	v_cvt_pk_bf16_f32 v94, v95, v94
	ds_write_b32 v101, v94 offset:56064
.LBB0_1414:
	v_sub_f32_e32 v94, v96, v76
	v_sub_f32_e32 v95, v97, v77
	v_cndmask_b32_e64 v96, 0, 1, s[62:63]
	v_min_f32_e32 v94, 0, v94
	v_min_f32_e32 v95, 0, v95
	v_mul_f32_e32 v94, 0x3fb8aa3b, v94
	v_mul_f32_e32 v95, 0x3fb8aa3b, v95
	v_exp_f32_e32 v94, v94
	v_exp_f32_e32 v95, v95
	v_cmp_ne_u32_e64 s[30:31], 1, v96
	s_andn2_b64 vcc, exec, s[62:63]
	s_cbranch_vccnz .LBB0_1416
	v_add_u32_e32 v96, 0x10e00, v101
	v_mul_f32_e32 v97, v95, v81
	v_mul_f32_e32 v101, v94, v79
	v_cvt_pk_bf16_f32 v97, v101, v97
	ds_write_b32 v96, v97
.LBB0_1416:
	v_add_f32_e32 v58, v58, v88
	v_add_f32_e32 v59, v59, v89
	v_lshlrev_b32_e32 v121, 16, v9
	v_mul_f32_e32 v96, 0x3fb8aa3b, v58
	v_mul_f32_e32 v97, 0x3fb8aa3b, v59
	v_exp_f32_e32 v96, v96
	v_exp_f32_e32 v97, v97
	v_sub_f32_e32 v58, v86, v58
	v_sub_f32_e32 v59, v87, v59
	v_and_b32_e32 v122, 0xffff0000, v9
	v_mul_f32_e32 v58, 0x3fb8aa3b, v58
	v_rcp_f32_e32 v101, v96
	v_rcp_f32_e32 v104, v97
	v_exp_f32_e32 v123, v58
	v_mul_f32_e32 v58, 0x3fb8aa3b, v59
	v_exp_f32_e32 v124, v58
	v_mul_f32_e32 v58, v96, v121
	v_mul_f32_e32 v59, v97, v122
	v_cvt_pk_bf16_f32 v96, v58, v59
	v_lshl_add_u32 v97, s5, 1, v120
	ds_write_b32 v97, v96 offset:8192
	v_mul_f32_e32 v96, v80, v58
	v_mul_f32_e32 v121, v78, v59
	v_cvt_pk_bf16_f32 v96, v96, v121
	v_mul_f32_e32 v58, v90, v58
	v_mul_f32_e32 v59, v92, v59
	v_min_f32_e32 v101, 0x79297b5a, v101
	v_min_f32_e32 v104, 0x79297b5a, v104
	ds_write_b32 v97, v96 offset:25600
	v_cvt_pk_bf16_f32 v96, v58, v59

	global_store_dword v62, v96, s[0:1]
	v_mul_f32_e32 v96, v101, v102
	v_mul_f32_e32 v97, v104, v105
	v_cvt_pk_bf16_f32 v96, v96, v97
	v_add_u32_e32 v97, s50, v120
	v_mul_f32_e32 v58, v123, v102
	v_mul_f32_e32 v59, v124, v105
	ds_write_b32 v97, v96 offset:43008
	s_and_b64 vcc, exec, s[26:27]
	v_add_u32_e32 v96, s49, v120
	s_cbranch_vccz .LBB0_1451
	s_and_b64 vcc, exec, s[28:29]
	s_cbranch_vccz .LBB0_1452

.LBB0_1420:
	v_add_f32_e32 v60, v60, v88
	v_add_f32_e32 v61, v61, v89
	v_lshlrev_b32_e32 v104, 16, v10
	v_mul_f32_e32 v96, 0x3fb8aa3b, v60
	v_mul_f32_e32 v97, 0x3fb8aa3b, v61
	v_exp_f32_e32 v96, v96
	v_exp_f32_e32 v97, v97
	v_sub_f32_e32 v60, v86, v60
	v_sub_f32_e32 v61, v87, v61
	v_and_b32_e32 v105, 0xffff0000, v10
	v_mul_f32_e32 v60, 0x3fb8aa3b, v60
	v_rcp_f32_e32 v101, v96
	v_rcp_f32_e32 v102, v97
	v_exp_f32_e32 v121, v60
	v_mul_f32_e32 v60, 0x3fb8aa3b, v61
	v_exp_f32_e32 v122, v60
	v_mul_f32_e32 v60, v96, v104
	v_mul_f32_e32 v61, v97, v105
	v_cvt_pk_bf16_f32 v96, v60, v61
	v_lshl_add_u32 v97, s83, 1, v120
	ds_write_b32 v97, v96 offset:8192
	v_mul_f32_e32 v96, v80, v60
	v_mul_f32_e32 v104, v78, v61
	v_cvt_pk_bf16_f32 v96, v96, v104
	v_mul_f32_e32 v60, v90, v60
	v_mul_f32_e32 v61, v92, v61
	v_min_f32_e32 v101, 0x79297b5a, v101
	v_min_f32_e32 v102, 0x79297b5a, v102
	ds_write_b32 v97, v96 offset:25600
	v_cvt_pk_bf16_f32 v96, v60, v61

	global_store_dword v62, v96, s[78:79]
	v_mul_f32_e32 v96, v101, v103
	v_mul_f32_e32 v97, v102, v107
	v_cvt_pk_bf16_f32 v96, v96, v97
	v_add_u32_e32 v97, s51, v120
	v_mul_f32_e32 v60, v121, v103
	v_mul_f32_e32 v61, v122, v107
	ds_write_b32 v97, v96 offset:43008
	s_and_b64 vcc, exec, s[26:27]
	v_add_u32_e32 v96, s91, v120
	s_cbranch_vccz .LBB0_1453
	s_and_b64 vcc, exec, s[28:29]
	s_cbranch_vccz .LBB0_1454

.LBB0_1424:
	v_add_f32_e32 v66, v66, v88
	v_add_f32_e32 v67, v67, v89
	v_lshlrev_b32_e32 v103, 16, v11
	v_mul_f32_e32 v96, 0x3fb8aa3b, v66
	v_mul_f32_e32 v97, 0x3fb8aa3b, v67
	v_exp_f32_e32 v96, v96
	v_exp_f32_e32 v97, v97
	v_sub_f32_e32 v66, v86, v66
	v_sub_f32_e32 v67, v87, v67
	v_and_b32_e32 v104, 0xffff0000, v11
	v_mul_f32_e32 v66, 0x3fb8aa3b, v66
	v_rcp_f32_e32 v101, v96
	v_rcp_f32_e32 v102, v97
	v_exp_f32_e32 v105, v66
	v_mul_f32_e32 v66, 0x3fb8aa3b, v67
	v_exp_f32_e32 v107, v66
	v_mul_f32_e32 v66, v96, v103
	v_mul_f32_e32 v67, v97, v104
	v_cvt_pk_bf16_f32 v96, v66, v67
	v_lshl_add_u32 v97, s97, 1, v120
	ds_write_b32 v97, v96 offset:8192
	v_mul_f32_e32 v96, v80, v66
	v_mul_f32_e32 v103, v78, v67
	v_cvt_pk_bf16_f32 v96, v96, v103
	v_mul_f32_e32 v66, v90, v66
	v_mul_f32_e32 v67, v92, v67
	v_min_f32_e32 v101, 0x79297b5a, v101
	v_min_f32_e32 v102, 0x79297b5a, v102
	ds_write_b32 v97, v96 offset:25600
	v_cvt_pk_bf16_f32 v96, v66, v67

	global_store_dword v62, v96, s[68:69]
	v_mul_f32_e32 v96, v101, v106
	v_mul_f32_e32 v97, v102, v109
	v_cvt_pk_bf16_f32 v96, v96, v97
	v_add_u32_e32 v97, s89, v120
	v_mul_f32_e32 v66, v105, v106
	v_mul_f32_e32 v67, v107, v109
	ds_write_b32 v97, v96 offset:43008
	s_and_b64 vcc, exec, s[26:27]
	v_add_u32_e32 v96, s48, v120
	s_cbranch_vccz .LBB0_1455
	s_and_b64 vcc, exec, s[28:29]
	s_cbranch_vccz .LBB0_1456

.LBB0_1428:
	v_add_f32_e32 v68, v68, v88
	v_add_f32_e32 v69, v69, v89
	v_lshlrev_b32_e32 v103, 16, v12
	v_mul_f32_e32 v96, 0x3fb8aa3b, v68
	v_mul_f32_e32 v97, 0x3fb8aa3b, v69
	v_exp_f32_e32 v96, v96
	v_exp_f32_e32 v97, v97
	v_sub_f32_e32 v68, v86, v68
	v_sub_f32_e32 v69, v87, v69
	v_and_b32_e32 v104, 0xffff0000, v12
	v_mul_f32_e32 v68, 0x3fb8aa3b, v68
	v_rcp_f32_e32 v101, v96
	v_rcp_f32_e32 v102, v97
	v_exp_f32_e32 v105, v68
	v_mul_f32_e32 v68, 0x3fb8aa3b, v69
	v_exp_f32_e32 v106, v68
	v_mul_f32_e32 v68, v96, v103
	v_mul_f32_e32 v69, v97, v104
	v_cvt_pk_bf16_f32 v96, v68, v69
	v_lshl_add_u32 v97, s57, 1, v120
	ds_write_b32 v97, v96 offset:8192
	v_mul_f32_e32 v96, v80, v68
	v_mul_f32_e32 v103, v78, v69
	v_cvt_pk_bf16_f32 v96, v96, v103
	v_mul_f32_e32 v68, v90, v68
	v_mul_f32_e32 v69, v92, v69
	v_min_f32_e32 v101, 0x79297b5a, v101
	v_min_f32_e32 v102, 0x79297b5a, v102
	ds_write_b32 v97, v96 offset:25600
	v_cvt_pk_bf16_f32 v96, v68, v69

	global_store_dword v62, v96, s[42:43]
	v_mul_f32_e32 v96, v101, v108
	v_mul_f32_e32 v97, v102, v112
	v_cvt_pk_bf16_f32 v96, v96, v97
	v_add_u32_e32 v97, s66, v120
	v_mul_f32_e32 v68, v105, v108
	v_mul_f32_e32 v69, v106, v112
	ds_write_b32 v97, v96 offset:43008
	s_and_b64 vcc, exec, s[26:27]
	v_add_u32_e32 v96, s96, v120
	s_cbranch_vccz .LBB0_1457
	s_and_b64 vcc, exec, s[28:29]
	s_cbranch_vccz .LBB0_1458

.LBB0_1432:
	v_add_f32_e32 v70, v70, v88
	v_add_f32_e32 v71, v71, v89
	v_lshlrev_b32_e32 v103, 16, v13
	v_mul_f32_e32 v96, 0x3fb8aa3b, v70
	v_mul_f32_e32 v97, 0x3fb8aa3b, v71
	v_exp_f32_e32 v96, v96
	v_exp_f32_e32 v97, v97
	v_sub_f32_e32 v70, v86, v70
	v_sub_f32_e32 v71, v87, v71
	v_and_b32_e32 v104, 0xffff0000, v13
	v_mul_f32_e32 v70, 0x3fb8aa3b, v70
	v_rcp_f32_e32 v101, v96
	v_rcp_f32_e32 v102, v97
	v_exp_f32_e32 v105, v70
	v_mul_f32_e32 v70, 0x3fb8aa3b, v71
	v_exp_f32_e32 v106, v70
	v_mul_f32_e32 v70, v96, v103
	v_mul_f32_e32 v71, v97, v104
	v_cvt_pk_bf16_f32 v96, v70, v71
	v_lshl_add_u32 v97, s46, 1, v120
	ds_write_b32 v97, v96 offset:8192
	v_mul_f32_e32 v96, v80, v70
	v_mul_f32_e32 v103, v78, v71
	v_cvt_pk_bf16_f32 v96, v96, v103
	v_mul_f32_e32 v70, v90, v70
	v_mul_f32_e32 v71, v92, v71
	v_min_f32_e32 v101, 0x79297b5a, v101
	v_min_f32_e32 v102, 0x79297b5a, v102
	ds_write_b32 v97, v96 offset:25600
	v_cvt_pk_bf16_f32 v96, v70, v71

	global_store_dword v62, v96, s[94:95]
	v_mul_f32_e32 v96, v101, v110
	v_mul_f32_e32 v97, v102, v114
	v_cvt_pk_bf16_f32 v96, v96, v97
	v_add_u32_e32 v97, s67, v120
	v_mul_f32_e32 v70, v105, v110
	v_mul_f32_e32 v71, v106, v114
	ds_write_b32 v97, v96 offset:43008
	s_and_b64 vcc, exec, s[26:27]
	v_add_u32_e32 v96, s4, v120
	s_cbranch_vccz .LBB0_1459
	s_and_b64 vcc, exec, s[28:29]
	s_cbranch_vccz .LBB0_1460

.LBB0_1436:
	v_add_f32_e32 v72, v88, v72
	v_add_f32_e32 v73, v89, v73
	v_lshlrev_b32_e32 v103, 16, v14
	v_mul_f32_e32 v96, 0x3fb8aa3b, v72
	v_mul_f32_e32 v97, 0x3fb8aa3b, v73
	v_exp_f32_e32 v96, v96
	v_exp_f32_e32 v97, v97
	v_sub_f32_e32 v72, v86, v72
	v_sub_f32_e32 v73, v87, v73
	v_and_b32_e32 v104, 0xffff0000, v14
	v_mul_f32_e32 v72, 0x3fb8aa3b, v72
	v_rcp_f32_e32 v101, v96
	v_rcp_f32_e32 v102, v97
	v_exp_f32_e32 v105, v72
	v_mul_f32_e32 v72, 0x3fb8aa3b, v73
	v_exp_f32_e32 v106, v72
	v_mul_f32_e32 v72, v96, v103
	v_mul_f32_e32 v73, v97, v104
	v_cvt_pk_bf16_f32 v96, v72, v73
	v_lshl_add_u32 v97, s47, 1, v120
	ds_write_b32 v97, v96 offset:8192
	v_mul_f32_e32 v96, v80, v72
	v_mul_f32_e32 v103, v78, v73
	v_cvt_pk_bf16_f32 v96, v96, v103
	v_mul_f32_e32 v72, v90, v72
	v_mul_f32_e32 v73, v92, v73
	v_min_f32_e32 v101, 0x79297b5a, v101
	v_min_f32_e32 v102, 0x79297b5a, v102
	ds_write_b32 v97, v96 offset:25600
	v_cvt_pk_bf16_f32 v96, v72, v73

	global_store_dword v62, v96, s[44:45]
	v_mul_f32_e32 v96, v101, v113
	v_mul_f32_e32 v97, v102, v116
	v_cvt_pk_bf16_f32 v96, v96, v97
	v_add_u32_e32 v97, s87, v120
	v_mul_f32_e32 v72, v105, v113
	v_mul_f32_e32 v73, v106, v116
	ds_write_b32 v97, v96 offset:43008
	s_and_b64 vcc, exec, s[26:27]
	v_add_u32_e32 v96, s40, v120
	s_cbranch_vccz .LBB0_1461
	s_and_b64 vcc, exec, s[28:29]
	s_cbranch_vccz .LBB0_1462

.LBB0_1440:
	v_add_f32_e32 v74, v88, v74
	v_add_f32_e32 v75, v89, v75
	v_and_b32_e32 v102, 0xffff0000, v15
	v_mul_f32_e32 v88, 0x3fb8aa3b, v74
	v_mul_f32_e32 v89, 0x3fb8aa3b, v75
	v_exp_f32_e32 v88, v88
	v_exp_f32_e32 v89, v89
	v_sub_f32_e32 v74, v86, v74
	v_sub_f32_e32 v75, v87, v75
	v_lshlrev_b32_e32 v101, 16, v15
	v_rcp_f32_e32 v96, v88
	v_rcp_f32_e32 v97, v89
	v_mul_f32_e32 v74, 0x3fb8aa3b, v74
	v_exp_f32_e32 v86, v74
	v_mul_f32_e32 v74, 0x3fb8aa3b, v75
	v_mul_f32_e32 v75, v89, v102
	v_exp_f32_e32 v87, v74
	v_mul_f32_e32 v74, v88, v101
	v_lshl_add_u32 v89, s41, 1, v120
	v_mul_f32_e32 v78, v78, v75
	v_cvt_pk_bf16_f32 v88, v74, v75
	ds_write_b32 v89, v88 offset:8192
	v_mul_f32_e32 v80, v80, v74
	v_cvt_pk_bf16_f32 v78, v80, v78
	v_mul_f32_e32 v74, v90, v74
	v_mul_f32_e32 v75, v92, v75
	v_min_f32_e32 v96, 0x79297b5a, v96
	v_min_f32_e32 v97, 0x79297b5a, v97
	ds_write_b32 v89, v78 offset:25600
	v_cvt_pk_bf16_f32 v78, v74, v75

	global_store_dword v62, v78, s[92:93]
	v_mul_f32_e32 v78, v96, v115
	v_mul_f32_e32 v80, v97, v117
	v_cvt_pk_bf16_f32 v78, v78, v80
	v_add_u32_e32 v80, s72, v120
	v_mul_f32_e32 v74, v86, v115
	v_mul_f32_e32 v75, v87, v117
	ds_write_b32 v80, v78 offset:43008
	s_and_b64 vcc, exec, s[26:27]
	v_add_u32_e32 v78, s90, v120
	s_cbranch_vccz .LBB0_1463
	s_and_b64 vcc, exec, s[28:29]
	s_cbranch_vccz .LBB0_1464

.LBB0_1444:
	v_sub_f32_e32 v76, v64, v76
	v_sub_f32_e32 v77, v65, v77
	v_mul_u32_u24_e32 v0, s73, v0
	v_mul_f32_e32 v76, 0x3fb8aa3b, v76
	v_mul_f32_e32 v77, 0x3fb8aa3b, v77
	v_exp_f32_e32 v76, v76
	v_exp_f32_e32 v77, v77
	s_mov_b32 s2, 0xffff
	s_andn2_b64 vcc, exec, s[54:55]
	v_mul_f32_e32 v70, v76, v70
	v_mul_f32_e32 v60, v76, v60
	v_mul_f32_e32 v78, v77, v61
	v_mul_f32_e32 v58, v76, v58
	v_mul_f32_e32 v80, v77, v59
	v_mul_f32_e32 v59, v76, v79
	v_mul_f32_e32 v61, v76, v74
	v_mul_f32_e32 v72, v76, v72
	v_mul_f32_e32 v68, v76, v68
	v_mul_f32_e32 v69, v77, v69
	v_mul_f32_e32 v66, v76, v66
	v_mul_f32_e32 v67, v77, v67
	v_cvt_pk_bf16_f32 v58, v59, v58
	v_cvt_pk_bf16_f32 v59, v60, v66
	v_cvt_pk_bf16_f32 v60, v68, v70
	v_cvt_pk_bf16_f32 v61, v72, v61
	v_add_u32_e32 v70, s84, v0
	v_mul_f32_e32 v73, v77, v73
	v_mul_f32_e32 v71, v77, v71
	v_mul_f32_e32 v79, v77, v81
	v_mul_f32_e32 v74, v77, v75
	v_cvt_pk_bf16_f32 v66, v79, v80
	v_cvt_pk_bf16_f32 v67, v78, v67
	v_cvt_pk_bf16_f32 v68, v69, v71
	v_cvt_pk_bf16_f32 v69, v73, v74
	ds_write_b128 v70, v[58:61]
	ds_write_b128 v70, v[66:69] offset:144
	v_lshlrev_b32_e32 v58, 16, v3
	v_lshlrev_b32_e32 v59, 16, v5
	v_lshlrev_b32_e32 v60, 16, v7
	s_waitcnt vmcnt(8)
	v_lshlrev_b32_e32 v61, 16, v25
	v_and_or_b32 v58, v2, s2, v58
	v_and_or_b32 v59, v4, s2, v59
	v_and_or_b32 v60, v6, s2, v60
	v_and_or_b32 v61, v24, s2, v61
	v_lshrrev_b32_e32 v66, 16, v2
	s_mov_b32 s2, 0xffff0000
	v_lshrrev_b32_e32 v67, 16, v4
	v_lshrrev_b32_e32 v68, 16, v6
	v_lshrrev_b32_e32 v69, 16, v24
	v_and_or_b32 v66, v3, s2, v66
	v_and_or_b32 v67, v5, s2, v67
	v_and_or_b32 v68, v7, s2, v68
	v_and_or_b32 v69, v25, s2, v69
	v_add_u32_e32 v0, s85, v0
	ds_write_b128 v0, v[58:61]
	ds_write_b128 v0, v[66:69] offset:144
	s_cbranch_vccnz .LBB0_1446
	v_mul_f32_e32 v0, 0x3fb8aa3b, v64
	v_exp_f32_e32 v58, v0
	v_mul_f32_e32 v0, 0x3fb8aa3b, v65
	v_exp_f32_e32 v59, v0
	ds_write_b64 v111, v[58:59] offset:6144
